# first XCD grid barrier: the 16 per-XCD counter loads of xcd_barrier_complete issued together (one base + immediate offsets) instead of 16 serial load/wait pairs
# speedup vs baseline: 1.0118x; 1.0008x over previous
; DI unsigned xb_ld(unsigned* p)              { return __hip_atomic_load(p, __ATOMIC_RELAXED, __HIP_MEMORY_SCOPE_AGENT); }
; DI void xcd_barrier_complete(unsigned* bar, unsigned x, unsigned& nloc, unsigned& nx) {
;     ...
;     for (;;) {
;         sum = 0u; cnt = 0u; mine = 0u;
; #pragma unroll
;         for (unsigned j = 0; j < 16; ++j) { const unsigned c = xb_ld(&bar[XB_XCNT(j)]); sum += c; cnt += (c > 0u) ? 1u : 0u; mine = (j == x) ? c : mine; }
;         if (sum == G) break;
;         __builtin_amdgcn_s_sleep(1);
;         if ((++sp & 255u) == 0u) { if (xb_ld(&bar[XB_TMO])) break; if (sp > XB_SPIN_CAP) { atomicAdd(&bar[XB_TMO], 1u); break; } }
;     }
;     nloc = mine > 0u ? mine : 1u; nx = cnt > 0u ? cnt : 1u;
.LBB0_93:
	v_readlane_b32 s4, v252, 4
	v_readlane_b32 s5, v252, 5
	v_readlane_b32 s3, v252, 1
	s_mov_b64 s[6:7], -1
	s_waitcnt lgkmcnt(0)
	s_nop 4
	global_load_dword v0, v16, s[4:5] sc1
	global_load_dword v1, v16, s[4:5] offset:256 sc1
	global_load_dword v2, v16, s[4:5] offset:512 sc1
	global_load_dword v3, v16, s[4:5] offset:768 sc1
	global_load_dword v4, v16, s[4:5] offset:1024 sc1
	global_load_dword v5, v16, s[4:5] offset:1280 sc1
	global_load_dword v6, v16, s[4:5] offset:1536 sc1
	global_load_dword v7, v16, s[4:5] offset:1792 sc1
	global_load_dword v8, v16, s[4:5] offset:2048 sc1
	global_load_dword v9, v16, s[4:5] offset:2304 sc1
	global_load_dword v10, v16, s[4:5] offset:2560 sc1
	global_load_dword v11, v16, s[4:5] offset:2816 sc1
	global_load_dword v12, v16, s[4:5] offset:3072 sc1
	global_load_dword v13, v16, s[4:5] offset:3328 sc1
	global_load_dword v14, v16, s[4:5] offset:3584 sc1
	global_load_dword v15, v16, s[4:5] offset:3840 sc1
	s_waitcnt vmcnt(0)
	s_mov_b64 s[4:5], -1
	v_add_u32_e32 v17, v1, v0
	v_add_u32_e32 v17, v17, v2
	v_add_u32_e32 v17, v17, v3
	v_add_u32_e32 v17, v17, v4
	v_add_u32_e32 v17, v17, v5
	v_add_u32_e32 v17, v17, v6
	v_add_u32_e32 v17, v17, v7
	v_add_u32_e32 v17, v17, v8
	v_add_u32_e32 v17, v17, v9
	v_add_u32_e32 v17, v17, v10
	v_add_u32_e32 v17, v17, v11
	v_add_u32_e32 v17, v17, v12
	v_add_u32_e32 v17, v17, v13
	v_add_u32_e32 v17, v17, v14
	v_add_u32_e32 v17, v17, v15
	s_nop 0
	v_cmp_eq_u32_e32 vcc, s3, v17
	s_cbranch_vccnz .LBB0_92
	s_and_b32 s3, s2, 0xff
	s_cmp_eq_u32 s3, 0
	s_mov_b64 s[8:9], -1
	s_sleep 1
	s_cbranch_scc1 .LBB0_97
	s_and_b64 vcc, exec, s[8:9]
	s_cbranch_vccz .LBB0_92
.LBB0_96:
	s_add_i32 s2, s2, 1
	s_mov_b64 s[6:7], 0
	s_branch .LBB0_92
	s_nop 0
	s_nop 0
	s_nop 0
	s_nop 0
	s_nop 0
	s_nop 0
	s_nop 0
	s_nop 0
